# swish gate (M3) and GLA gate loop: v_rcp_f32 + v_mul_f32 instead of the 11-instruction IEEE division sequence (70 sites)
# baseline (speedup 1.0000x reference)
.LBB0_425:
	v_readlane_b32 s6, v4, s5
	v_readlane_b32 s7, v5, s5
	v_readlane_b32 s8, v6, s5
	v_readlane_b32 s9, v7, s5
	v_pk_fma_f32 v[18:19], v[24:25], s[6:7], v[192:193]
	v_readlane_b32 s10, v0, s5
	v_readlane_b32 s11, v1, s5
	v_pk_fma_f32 v[18:19], v[26:27], s[8:9], v[18:19]
	v_readlane_b32 s22, v2, s5
	v_readlane_b32 s23, v3, s5
	v_pk_fma_f32 v[18:19], v[28:29], s[10:11], v[18:19]
	v_readlane_b32 s30, v12, s5
	v_readlane_b32 s31, v13, s5
	v_pk_fma_f32 v[18:19], v[30:31], s[22:23], v[18:19]
	v_readlane_b32 s34, v14, s5
	v_readlane_b32 s35, v15, s5
	v_pk_fma_f32 v[18:19], v[34:35], s[30:31], v[18:19]
	v_readlane_b32 s38, v8, s5
	v_readlane_b32 s39, v9, s5
	v_pk_fma_f32 v[18:19], v[36:37], s[34:35], v[18:19]
	v_readlane_b32 s56, v10, s5
	v_readlane_b32 s57, v11, s5
	v_pk_fma_f32 v[18:19], v[38:39], s[38:39], v[18:19]
	s_add_i32 s12, s5, 1
	v_pk_fma_f32 v[18:19], v[40:41], s[56:57], v[18:19]
	v_readlane_b32 s8, v6, s12
	v_add_f32_e32 v18, v18, v19
	v_min_f32_e32 v19, 0, v18
	v_mul_f32_e64 v18, |v18|, s87
	v_exp_f32_e32 v18, v18
	v_readlane_b32 s9, v7, s12
	v_readlane_b32 s10, v0, s12
	v_readlane_b32 s11, v1, s12
	v_add_f32_e32 v18, 1.0, v18
	v_cmp_gt_f32_e32 vcc, s86, v18
	v_readlane_b32 s22, v2, s12
	v_readlane_b32 s23, v3, s12
	v_cndmask_b32_e64 v20, 0, 32, vcc
	v_ldexp_f32 v18, v18, v20
	v_log_f32_e32 v18, v18
	v_readlane_b32 s30, v12, s12
	v_readlane_b32 s31, v13, s12
	v_readlane_b32 s34, v14, s12
	v_mul_f32_e32 v20, 0x3f317217, v18
	v_fma_f32 v20, v18, s88, -v20
	v_fmac_f32_e32 v20, 0x3377d1cf, v18
	v_fmac_f32_e32 v20, 0x3f317217, v18
	v_cmp_lt_f32_e64 s[56:57], |v18|, s89
	v_readlane_b32 s35, v15, s12
	v_readlane_b32 s38, v8, s12
	v_cndmask_b32_e64 v18, v18, v20, s[56:57]
	v_cndmask_b32_e32 v20, 0, v239, vcc
	v_sub_f32_e32 v18, v18, v20
	v_sub_f32_e32 v18, v19, v18
	v_fmac_f32_e32 v17, 0x3d800000, v18
	ds_read_u16 v19, v16
	v_mul_f32_e32 v18, 0x3fb8aa3b, v17
	v_exp_f32_e32 v18, v18
	v_readlane_b32 s39, v9, s12
	v_readlane_b32 s56, v10, s12
	s_waitcnt lgkmcnt(0)
	v_lshlrev_b32_e32 v19, 16, v19
	v_readlane_b32 s6, v4, s12
	v_readlane_b32 s7, v5, s12
	v_readlane_b32 s57, v11, s12
	s_nop 0
	v_rcp_f32_e32 v20, v18
	s_nop 0
	v_mul_f32_e32 v19, v19, v20
	s_nop 0
	v_cvt_pk_bf16_f32 v19, v19, s0
	ds_write_b16 v16, v19
	ds_read_u16 v19, v16 offset:9216
	s_add_i32 s12, s5, 2
	s_waitcnt lgkmcnt(0)
	v_lshlrev_b32_e32 v19, 16, v19
	v_mul_f32_e32 v19, 0x3e000000, v19
	v_mul_f32_e32 v18, v19, v18
	v_cvt_pk_bf16_f32 v18, v18, s0
	ds_write_b16 v16, v18 offset:9216
	v_pk_fma_f32 v[18:19], v[24:25], s[6:7], v[192:193]
	s_nop 0
	v_pk_fma_f32 v[18:19], v[26:27], s[8:9], v[18:19]
	v_readlane_b32 s8, v6, s12
	v_pk_fma_f32 v[18:19], v[28:29], s[10:11], v[18:19]
	v_readlane_b32 s9, v7, s12
	v_pk_fma_f32 v[18:19], v[30:31], s[22:23], v[18:19]
	v_readlane_b32 s10, v0, s12
	v_pk_fma_f32 v[18:19], v[34:35], s[30:31], v[18:19]
	v_readlane_b32 s11, v1, s12
	v_pk_fma_f32 v[18:19], v[36:37], s[34:35], v[18:19]
	v_readlane_b32 s22, v2, s12
	v_pk_fma_f32 v[18:19], v[38:39], s[38:39], v[18:19]
	v_readlane_b32 s23, v3, s12
	v_pk_fma_f32 v[18:19], v[40:41], s[56:57], v[18:19]
	v_readlane_b32 s30, v12, s12
	v_add_f32_e32 v18, v18, v19
	v_min_f32_e32 v19, 0, v18
	v_mul_f32_e64 v18, |v18|, s87
	v_exp_f32_e32 v18, v18
	v_readlane_b32 s31, v13, s12
	v_readlane_b32 s34, v14, s12
	v_readlane_b32 s35, v15, s12
	v_add_f32_e32 v18, 1.0, v18
	v_cmp_gt_f32_e32 vcc, s86, v18
	v_readlane_b32 s38, v8, s12
	v_readlane_b32 s39, v9, s12
	v_cndmask_b32_e64 v20, 0, 32, vcc
	v_ldexp_f32 v18, v18, v20
	v_log_f32_e32 v18, v18
	s_nop 0
	v_mul_f32_e32 v20, 0x3f317217, v18
	v_fma_f32 v20, v18, s88, -v20
	v_fmac_f32_e32 v20, 0x3377d1cf, v18
	v_fmac_f32_e32 v20, 0x3f317217, v18
	v_cmp_lt_f32_e64 s[56:57], |v18|, s89
	s_nop 1
	v_cndmask_b32_e64 v18, v18, v20, s[56:57]
	v_cndmask_b32_e32 v20, 0, v239, vcc
	v_sub_f32_e32 v18, v18, v20
	v_sub_f32_e32 v18, v19, v18
	v_fmac_f32_e32 v17, 0x3d800000, v18
	ds_read_u16 v19, v16 offset:144
	v_mul_f32_e32 v18, 0x3fb8aa3b, v17
	v_exp_f32_e32 v18, v18
	v_readlane_b32 s56, v10, s12
	v_readlane_b32 s57, v11, s12
	s_waitcnt lgkmcnt(0)
	v_lshlrev_b32_e32 v19, 16, v19
	v_readlane_b32 s6, v4, s12
	v_readlane_b32 s7, v5, s12
	s_add_i32 s12, s5, 3
	s_nop 0
	v_rcp_f32_e32 v20, v18
	s_nop 0
	v_mul_f32_e32 v19, v19, v20
	s_nop 0
	v_cvt_pk_bf16_f32 v19, v19, s0
	ds_write_b16 v16, v19 offset:144
	ds_read_u16 v19, v16 offset:9360
	s_add_i32 s5, s5, 4
	s_cmp_eq_u32 s5, 64
	s_waitcnt lgkmcnt(0)
	v_lshlrev_b32_e32 v19, 16, v19
	v_mul_f32_e32 v19, 0x3e000000, v19
	v_mul_f32_e32 v18, v19, v18
	v_cvt_pk_bf16_f32 v18, v18, s0
	ds_write_b16 v16, v18 offset:9360
	v_pk_fma_f32 v[18:19], v[24:25], s[6:7], v[192:193]
	s_nop 0
	v_pk_fma_f32 v[18:19], v[26:27], s[8:9], v[18:19]
	v_readlane_b32 s8, v6, s12
	v_pk_fma_f32 v[18:19], v[28:29], s[10:11], v[18:19]
	v_readlane_b32 s9, v7, s12
	v_pk_fma_f32 v[18:19], v[30:31], s[22:23], v[18:19]
	v_readlane_b32 s10, v0, s12
	v_pk_fma_f32 v[18:19], v[34:35], s[30:31], v[18:19]
	v_readlane_b32 s11, v1, s12
	v_pk_fma_f32 v[18:19], v[36:37], s[34:35], v[18:19]
	v_readlane_b32 s22, v2, s12
	v_pk_fma_f32 v[18:19], v[38:39], s[38:39], v[18:19]
	v_readlane_b32 s23, v3, s12
	v_pk_fma_f32 v[18:19], v[40:41], s[56:57], v[18:19]
	v_readlane_b32 s30, v12, s12
	v_add_f32_e32 v18, v18, v19
	v_min_f32_e32 v19, 0, v18
	v_mul_f32_e64 v18, |v18|, s87
	v_exp_f32_e32 v18, v18
	v_readlane_b32 s31, v13, s12
	v_readlane_b32 s34, v14, s12
	v_readlane_b32 s35, v15, s12
	v_add_f32_e32 v18, 1.0, v18
	v_cmp_gt_f32_e32 vcc, s86, v18
	v_readlane_b32 s38, v8, s12
	v_readlane_b32 s39, v9, s12
	v_cndmask_b32_e64 v20, 0, 32, vcc
	v_ldexp_f32 v18, v18, v20
	v_log_f32_e32 v18, v18
	s_nop 0
	v_mul_f32_e32 v20, 0x3f317217, v18
	v_fma_f32 v20, v18, s88, -v20
	v_fmac_f32_e32 v20, 0x3377d1cf, v18
	v_fmac_f32_e32 v20, 0x3f317217, v18
	v_cmp_lt_f32_e64 s[56:57], |v18|, s89
	s_nop 1
	v_cndmask_b32_e64 v18, v18, v20, s[56:57]
	v_cndmask_b32_e32 v20, 0, v239, vcc
	v_sub_f32_e32 v18, v18, v20
	v_sub_f32_e32 v18, v19, v18
	v_fmac_f32_e32 v17, 0x3d800000, v18
	ds_read_u16 v19, v16 offset:288
	v_mul_f32_e32 v18, 0x3fb8aa3b, v17
	v_exp_f32_e32 v18, v18
	v_readlane_b32 s56, v10, s12
	v_readlane_b32 s57, v11, s12
	s_waitcnt lgkmcnt(0)
	v_lshlrev_b32_e32 v19, 16, v19
	v_readlane_b32 s6, v4, s12
	v_readlane_b32 s7, v5, s12
	s_nop 0
	v_rcp_f32_e32 v20, v18
	s_nop 0
	v_mul_f32_e32 v19, v19, v20
	s_nop 0
	v_cvt_pk_bf16_f32 v19, v19, s0
	ds_write_b16 v16, v19 offset:288
	ds_read_u16 v19, v16 offset:9504
	s_waitcnt lgkmcnt(0)
	v_lshlrev_b32_e32 v19, 16, v19
	v_mul_f32_e32 v19, 0x3e000000, v19
	v_mul_f32_e32 v18, v19, v18
	v_cvt_pk_bf16_f32 v18, v18, s0
	ds_write_b16 v16, v18 offset:9504
	v_pk_fma_f32 v[18:19], v[24:25], s[6:7], v[192:193]
	s_nop 0
	v_pk_fma_f32 v[18:19], v[26:27], s[8:9], v[18:19]
	s_nop 0
	v_pk_fma_f32 v[18:19], v[28:29], s[10:11], v[18:19]
	s_nop 0
	v_pk_fma_f32 v[18:19], v[30:31], s[22:23], v[18:19]
	s_nop 0
	v_pk_fma_f32 v[18:19], v[34:35], s[30:31], v[18:19]
	s_nop 0
	v_pk_fma_f32 v[18:19], v[36:37], s[34:35], v[18:19]
	s_nop 0
	v_pk_fma_f32 v[18:19], v[38:39], s[38:39], v[18:19]
	s_nop 0
	v_pk_fma_f32 v[18:19], v[40:41], s[56:57], v[18:19]
	s_nop 0
	v_add_f32_e32 v18, v18, v19
	v_min_f32_e32 v19, 0, v18
	v_mul_f32_e64 v18, |v18|, s87
	v_exp_f32_e32 v18, v18
	s_nop 0
	v_add_f32_e32 v18, 1.0, v18
	v_cmp_gt_f32_e32 vcc, s86, v18
	s_nop 1
	v_cndmask_b32_e64 v20, 0, 32, vcc
	v_ldexp_f32 v18, v18, v20
	v_log_f32_e32 v18, v18
	s_nop 0
	v_mul_f32_e32 v20, 0x3f317217, v18
	v_fma_f32 v20, v18, s88, -v20
	v_fmac_f32_e32 v20, 0x3377d1cf, v18
	v_fmac_f32_e32 v20, 0x3f317217, v18
	v_cmp_lt_f32_e64 s[56:57], |v18|, s89
	s_nop 1
	v_cndmask_b32_e64 v18, v18, v20, s[56:57]
	v_cndmask_b32_e32 v20, 0, v239, vcc
	v_sub_f32_e32 v18, v18, v20
	v_sub_f32_e32 v18, v19, v18
	v_fmac_f32_e32 v17, 0x3d800000, v18
	v_mul_f32_e32 v18, 0x3fb8aa3b, v17
	v_exp_f32_e32 v68, v18
	ds_read_u16 v18, v16 offset:432
	s_waitcnt lgkmcnt(0)
	v_lshlrev_b32_e32 v18, 16, v18
	s_nop 0
	s_nop 0
	v_rcp_f32_e32 v19, v68
	s_nop 0
	v_mul_f32_e32 v18, v18, v19
	s_nop 0
	v_cvt_pk_bf16_f32 v18, v18, s0
	ds_write_b16 v16, v18 offset:432
	ds_read_u16 v18, v16 offset:9648
	s_waitcnt lgkmcnt(0)
	v_lshlrev_b32_e32 v18, 16, v18
	v_mul_f32_e32 v18, 0x3e000000, v18
	v_mul_f32_e32 v18, v18, v68
	v_cvt_pk_bf16_f32 v18, v18, s0
	ds_write_b16 v16, v18 offset:9648
	v_add_u32_e32 v16, 0x240, v16
	s_cbranch_scc0 .LBB0_425
	s_waitcnt lgkmcnt(0)
	v_mad_i64_i32 v[0:1], s[6:7], v42, s84, v[22:23]
	v_mad_i64_i32 v[2:3], s[6:7], v33, s84, v[22:23]
	v_mad_i64_i32 v[4:5], s[6:7], v44, s84, v[22:23]
	v_mad_i64_i32 v[6:7], s[6:7], v46, s84, v[22:23]
	v_mad_i64_i32 v[8:9], s[6:7], v48, s84, v[22:23]
	v_mad_i64_i32 v[10:11], s[6:7], v50, s84, v[22:23]
	v_mad_i64_i32 v[12:13], s[6:7], v52, s84, v[22:23]
	v_mad_i64_i32 v[14:15], s[6:7], v54, s84, v[22:23]
	ds_read_b128 v[160:163], v45 offset:9216
	ds_read_b128 v[164:167], v47 offset:9216
	ds_read_b128 v[168:171], v49 offset:9216
	ds_read_b128 v[172:175], v51 offset:9216
	ds_read_b128 v[176:179], v53 offset:9216
	ds_read_b128 v[180:183], v55 offset:9216
	ds_read_b128 v[184:187], v56 offset:9216
	ds_read_b128 v[188:191], v57 offset:9216
	s_waitcnt lgkmcnt(7)
	global_store_dwordx4 v[0:1], v[160:163], off offset:2048
	ds_read_b128 v[96:99], v45
	s_waitcnt lgkmcnt(7)
	global_store_dwordx4 v[2:3], v[164:167], off offset:2048
	ds_read_b128 v[100:103], v47
	s_waitcnt lgkmcnt(7)
	global_store_dwordx4 v[4:5], v[168:171], off offset:2048
	ds_read_b128 v[104:107], v49
	s_waitcnt lgkmcnt(7)
	global_store_dwordx4 v[6:7], v[172:175], off offset:2048
	ds_read_b128 v[108:111], v51
	s_waitcnt lgkmcnt(7)
	global_store_dwordx4 v[8:9], v[176:179], off offset:2048
	ds_read_b128 v[112:115], v53
	s_waitcnt lgkmcnt(7)
	global_store_dwordx4 v[10:11], v[180:183], off offset:2048
	ds_read_b128 v[116:119], v55
	s_waitcnt lgkmcnt(7)
	global_store_dwordx4 v[12:13], v[184:187], off offset:2048
	ds_read_b128 v[120:123], v56
	s_waitcnt lgkmcnt(7)
	global_store_dwordx4 v[14:15], v[188:191], off offset:2048
	ds_read_b128 v[124:127], v57
	s_waitcnt lgkmcnt(7)
	global_store_dwordx4 v[0:1], v[96:99], off offset:2560
	s_waitcnt lgkmcnt(6)
	global_store_dwordx4 v[2:3], v[100:103], off offset:2560
	s_waitcnt lgkmcnt(5)
	global_store_dwordx4 v[4:5], v[104:107], off offset:2560
	s_waitcnt lgkmcnt(4)
	global_store_dwordx4 v[6:7], v[108:111], off offset:2560
	s_waitcnt lgkmcnt(3)
	global_store_dwordx4 v[8:9], v[112:115], off offset:2560
	s_waitcnt lgkmcnt(2)
	global_store_dwordx4 v[10:11], v[116:119], off offset:2560
	s_waitcnt lgkmcnt(1)
	global_store_dwordx4 v[12:13], v[120:123], off offset:2560
	s_waitcnt lgkmcnt(0)
	global_store_dwordx4 v[14:15], v[124:127], off offset:2560
	s_waitcnt vmcnt(16)
	ds_write_b128 v45, v[128:131] offset:9216
	ds_write_b128 v47, v[132:135] offset:9216
	ds_write_b128 v49, v[136:139] offset:9216
	ds_write_b128 v51, v[140:143] offset:9216
	ds_write_b128 v53, v[144:147] offset:9216
	ds_write_b128 v55, v[148:151] offset:9216
	ds_write_b128 v56, v[152:155] offset:9216
	ds_write_b128 v57, v[156:159] offset:9216
	s_mov_b64 s[34:35], 0

.LBB0_876:
	v_add_f32_e32 v32, 0x358637bd, v35
	v_cmp_gt_f32_e32 vcc, s73, v32
	v_mul_f32_e32 v33, 0x4f800000, v32
	v_ashrrev_i32_e32 v113, 31, v112
	v_cndmask_b32_e32 v32, v32, v33, vcc
	v_sqrt_f32_e32 v33, v32
	s_add_i32 s2, s2, s72
	s_cmpk_gt_i32 s2, 0xff
	s_waitcnt lgkmcnt(0)
	v_add_u32_e32 v34, -1, v33
	v_fma_f32 v35, -v34, v33, v32
	v_cmp_ge_f32_e64 s[38:39], 0, v35
	v_add_u32_e32 v35, 1, v33
	s_nop 0
	v_cndmask_b32_e64 v34, v33, v34, s[38:39]
	v_fma_f32 v33, -v35, v33, v32
	v_cmp_lt_f32_e64 s[38:39], 0, v33
	s_nop 1
	v_cndmask_b32_e64 v33, v34, v35, s[38:39]
	v_mul_f32_e32 v34, 0x37800000, v33
	v_cndmask_b32_e32 v33, v33, v34, vcc
	v_cmp_class_f32_e32 vcc, v32, v236
	s_nop 1
	v_cndmask_b32_e32 v32, v33, v32, vcc
	s_nop 0
	s_nop 0
	v_rcp_f32_e32 v38, v32
	s_nop 0
	v_mov_b64_e32 v[32:33], s[34:35]
	v_mad_i64_i32 v[32:33], s[4:5], v112, s84, v[32:33]
	v_lshlrev_b64 v[34:35], 11, v[112:113]
	v_lshl_add_u64 v[32:33], v[192:193], 1, v[32:33]
	v_lshl_add_u64 v[34:35], s[20:21], 0, v[34:35]
	v_lshl_add_u64 v[34:35], s[42:43], 1, v[34:35]
	v_lshl_add_u64 v[40:41], v[32:33], 0, v[70:71]
	v_lshl_add_u64 v[42:43], s[26:27], 1, v[34:35]
	global_load_dwordx2 v[44:45], v[40:41], off
	global_load_dwordx4 v[32:35], v[68:69], off
	global_load_dwordx2 v[156:157], v[40:41], off offset:16
	global_load_dwordx2 v[158:159], v[40:41], off offset:32
	global_load_dwordx2 v[160:161], v[40:41], off offset:48
	global_load_dwordx2 v[162:163], v[40:41], off offset:64
	global_load_dwordx2 v[164:165], v[40:41], off offset:80
	global_load_dwordx2 v[166:167], v[40:41], off offset:96
	global_load_dwordx2 v[168:169], v[40:41], off offset:112
	global_load_dwordx4 v[172:175], v[68:69], off offset:32
	global_load_dwordx4 v[176:179], v[68:69], off offset:64
	global_load_dwordx4 v[180:183], v[68:69], off offset:96
	global_load_dwordx4 v[184:187], v[68:69], off offset:128
	global_load_dwordx4 v[188:191], v[68:69], off offset:160
	global_load_dwordx4 v[206:209], v[68:69], off offset:192
	global_load_dwordx4 v[210:213], v[68:69], off offset:224
	v_pk_add_f32 v[16:17], v[16:17], v[36:37] op_sel_hi:[1,0] neg_lo:[0,1] neg_hi:[0,1]
	s_waitcnt vmcnt(15)
	v_and_b32_e32 v39, 0xffff0000, v44
	v_lshlrev_b32_e32 v37, 16, v44
	v_pk_mul_f32 v[16:17], v[16:17], v[38:39] op_sel_hi:[1,0]
	v_mul_f32_e32 v44, 0xbfb8aa3b, v37
	s_waitcnt vmcnt(14)
	v_pk_mul_f32 v[16:17], v[32:33], v[16:17]
	v_mul_f32_e32 v32, 0xbfb8aa3b, v39
	v_exp_f32_e32 v46, v44
	v_exp_f32_e32 v47, v32
	v_pk_add_f32 v[18:19], v[18:19], v[36:37] op_sel_hi:[1,0] neg_lo:[0,1] neg_hi:[0,1]
	v_pk_add_f32 v[32:33], v[46:47], 1.0 op_sel_hi:[1,0]
	s_nop 0
	s_nop 0
	s_nop 0
	v_rcp_f32_e32 v44, v33
	s_nop 0
	v_mul_f32_e32 v33, v39, v44
	s_nop 0
	s_nop 0
	s_nop 0
	v_rcp_f32_e32 v39, v32
	s_nop 0
	v_mul_f32_e32 v32, v37, v39
	s_nop 0
	v_lshlrev_b32_e32 v37, 16, v45
	v_and_b32_e32 v39, 0xffff0000, v45
	v_pk_mul_f32 v[16:17], v[16:17], v[32:33]
	v_mul_f32_e32 v32, 0xbfb8aa3b, v37
	v_mul_f32_e32 v33, 0xbfb8aa3b, v39
	v_exp_f32_e32 v32, v32
	v_exp_f32_e32 v33, v33
	v_pk_mul_f32 v[18:19], v[18:19], v[38:39] op_sel_hi:[1,0]
	v_pk_add_f32 v[32:33], v[32:33], 1.0 op_sel_hi:[1,0]
	v_pk_mul_f32 v[18:19], v[34:35], v[18:19]
	s_nop 0
	s_nop 0
	v_rcp_f32_e32 v34, v33
	s_nop 0
	v_mul_f32_e32 v33, v39, v34
	s_nop 0
	s_nop 0
	s_nop 0
	v_rcp_f32_e32 v34, v32
	s_nop 0
	v_mul_f32_e32 v32, v37, v34
	s_nop 0
	v_pk_mul_f32 v[18:19], v[18:19], v[32:33]
	v_cvt_pk_bf16_f32 v32, v16, v17
	v_cvt_pk_bf16_f32 v33, v18, v19
	v_lshl_add_u64 v[16:17], v[42:43], 0, v[70:71]
	global_store_dwordx2 v[16:17], v[32:33], off
	s_waitcnt vmcnt(1)
	v_mov_b64_e32 v[42:43], v[156:157]
	v_mov_b64_e32 v[32:33], v[172:173]
	v_mov_b64_e32 v[34:35], v[174:175]
	v_pk_add_f32 v[18:19], v[20:21], v[36:37] op_sel_hi:[1,0] neg_lo:[0,1] neg_hi:[0,1]
	v_lshlrev_b32_e32 v37, 16, v42
	v_and_b32_e32 v39, 0xffff0000, v42
	v_mul_f32_e32 v20, 0xbfb8aa3b, v37
	v_mul_f32_e32 v21, 0xbfb8aa3b, v39
	v_exp_f32_e32 v20, v20
	v_exp_f32_e32 v21, v21
	v_pk_mul_f32 v[18:19], v[18:19], v[38:39] op_sel_hi:[1,0]
	v_pk_add_f32 v[20:21], v[20:21], 1.0 op_sel_hi:[1,0]
	v_pk_mul_f32 v[18:19], v[18:19], v[32:33]
	s_nop 0
	s_nop 0
	v_rcp_f32_e32 v32, v21
	s_nop 0
	v_mul_f32_e32 v21, v39, v32
	s_nop 0
	s_nop 0
	s_nop 0
	v_rcp_f32_e32 v32, v20
	s_nop 0
	v_mul_f32_e32 v20, v37, v32
	s_nop 0
	v_lshlrev_b32_e32 v32, 16, v43
	v_and_b32_e32 v33, 0xffff0000, v43
	v_pk_mul_f32 v[18:19], v[18:19], v[20:21]
	v_pk_add_f32 v[20:21], v[22:23], v[36:37] op_sel_hi:[1,0] neg_lo:[0,1] neg_hi:[0,1]
	v_mul_f32_e32 v22, 0xbfb8aa3b, v32
	v_mul_f32_e32 v23, 0xbfb8aa3b, v33
	v_exp_f32_e32 v22, v22
	v_exp_f32_e32 v23, v23
	v_pk_mul_f32 v[20:21], v[20:21], v[38:39] op_sel_hi:[1,0]
	v_cvt_pk_bf16_f32 v18, v18, v19
	v_pk_mul_f32 v[20:21], v[20:21], v[34:35]
	v_pk_add_f32 v[22:23], v[22:23], 1.0 op_sel_hi:[1,0]
	s_nop 0
	s_nop 0
	s_nop 0
	v_rcp_f32_e32 v34, v23
	s_nop 0
	v_mul_f32_e32 v23, v33, v34
	s_nop 0
	s_nop 0
	s_nop 0
	v_rcp_f32_e32 v33, v22
	s_nop 0
	v_mul_f32_e32 v22, v32, v33
	s_nop 0
	v_pk_mul_f32 v[20:21], v[20:21], v[22:23]
	v_pk_add_f32 v[24:25], v[24:25], v[36:37] op_sel_hi:[1,0] neg_lo:[0,1] neg_hi:[0,1]
	v_cvt_pk_bf16_f32 v19, v20, v21
	global_store_dwordx2 v[16:17], v[18:19], off offset:16
	s_waitcnt vmcnt(2)
	v_mov_b64_e32 v[22:23], v[158:159]
	v_mov_b64_e32 v[18:19], v[176:177]
	v_mov_b64_e32 v[20:21], v[178:179]
	v_pk_mul_f32 v[24:25], v[24:25], v[38:39] op_sel_hi:[1,0]
	v_lshlrev_b32_e32 v34, 16, v22
	v_and_b32_e32 v22, 0xffff0000, v22
	v_mul_f32_e32 v32, 0xbfb8aa3b, v34
	v_pk_mul_f32 v[18:19], v[24:25], v[18:19]
	v_mul_f32_e32 v24, 0xbfb8aa3b, v22
	v_exp_f32_e32 v32, v32
	v_exp_f32_e32 v33, v24
	s_nop 0
	v_pk_add_f32 v[24:25], v[32:33], 1.0 op_sel_hi:[1,0]
	s_nop 0
	s_nop 0
	s_nop 0
	v_rcp_f32_e32 v32, v25
	s_nop 0
	v_mul_f32_e32 v25, v22, v32
	s_nop 0
	s_nop 0
	s_nop 0
	v_rcp_f32_e32 v22, v24
	s_nop 0
	v_mul_f32_e32 v24, v34, v22
	s_nop 0
	v_pk_mul_f32 v[18:19], v[18:19], v[24:25]
	v_pk_add_f32 v[24:25], v[26:27], v[36:37] op_sel_hi:[1,0] neg_lo:[0,1] neg_hi:[0,1]
	v_lshlrev_b32_e32 v26, 16, v23
	v_and_b32_e32 v27, 0xffff0000, v23
	v_mul_f32_e32 v22, 0xbfb8aa3b, v26
	v_mul_f32_e32 v23, 0xbfb8aa3b, v27
	v_exp_f32_e32 v22, v22
	v_exp_f32_e32 v23, v23
	v_pk_mul_f32 v[24:25], v[24:25], v[38:39] op_sel_hi:[1,0]
	v_cvt_pk_bf16_f32 v18, v18, v19
	v_pk_mul_f32 v[20:21], v[24:25], v[20:21]
	v_pk_add_f32 v[22:23], v[22:23], 1.0 op_sel_hi:[1,0]
	v_pk_add_f32 v[0:1], v[0:1], v[36:37] op_sel_hi:[1,0] neg_lo:[0,1] neg_hi:[0,1]
	v_pk_mul_f32 v[0:1], v[0:1], v[38:39] op_sel_hi:[1,0]
	v_pk_add_f32 v[2:3], v[2:3], v[36:37] op_sel_hi:[1,0] neg_lo:[0,1] neg_hi:[0,1]
	v_pk_add_f32 v[4:5], v[4:5], v[36:37] op_sel_hi:[1,0] neg_lo:[0,1] neg_hi:[0,1]
	s_nop 0
	v_rcp_f32_e32 v24, v23
	s_nop 0
	v_mul_f32_e32 v23, v27, v24
	s_nop 0
	v_pk_mul_f32 v[2:3], v[2:3], v[38:39] op_sel_hi:[1,0]
	v_pk_mul_f32 v[4:5], v[4:5], v[38:39] op_sel_hi:[1,0]
	s_nop 0
	v_rcp_f32_e32 v24, v22
	s_nop 0
	v_mul_f32_e32 v22, v26, v24
	s_nop 0
	v_pk_mul_f32 v[20:21], v[20:21], v[22:23]
	v_pk_add_f32 v[24:25], v[28:29], v[36:37] op_sel_hi:[1,0] neg_lo:[0,1] neg_hi:[0,1]
	v_cvt_pk_bf16_f32 v19, v20, v21
	global_store_dwordx2 v[16:17], v[18:19], off offset:32
	s_waitcnt vmcnt(3)
	v_mov_b64_e32 v[22:23], v[160:161]
	v_mov_b64_e32 v[18:19], v[180:181]
	v_mov_b64_e32 v[20:21], v[182:183]
	v_pk_mul_f32 v[24:25], v[24:25], v[38:39] op_sel_hi:[1,0]
	v_lshlrev_b32_e32 v28, 16, v22
	v_and_b32_e32 v22, 0xffff0000, v22
	v_mul_f32_e32 v26, 0xbfb8aa3b, v28
	v_pk_mul_f32 v[18:19], v[24:25], v[18:19]
	v_mul_f32_e32 v24, 0xbfb8aa3b, v22
	v_exp_f32_e32 v26, v26
	v_exp_f32_e32 v27, v24
	s_nop 0
	v_pk_add_f32 v[24:25], v[26:27], 1.0 op_sel_hi:[1,0]
	s_nop 0
	s_nop 0
	s_nop 0
	v_rcp_f32_e32 v26, v25
	s_nop 0
	v_mul_f32_e32 v25, v22, v26
	s_nop 0
	s_nop 0
	v_lshlrev_b32_e32 v26, 16, v23
	v_and_b32_e32 v27, 0xffff0000, v23
	s_nop 0
	v_rcp_f32_e32 v22, v24
	s_nop 0
	v_mul_f32_e32 v24, v28, v22
	s_nop 0
	v_mul_f32_e32 v22, 0xbfb8aa3b, v26
	v_mul_f32_e32 v23, 0xbfb8aa3b, v27
	v_exp_f32_e32 v22, v22
	v_exp_f32_e32 v23, v23
	v_pk_mul_f32 v[18:19], v[18:19], v[24:25]
	v_pk_add_f32 v[24:25], v[30:31], v[36:37] op_sel_hi:[1,0] neg_lo:[0,1] neg_hi:[0,1]
	v_cvt_pk_bf16_f32 v18, v18, v19
	v_pk_mul_f32 v[24:25], v[24:25], v[38:39] op_sel_hi:[1,0]
	v_pk_add_f32 v[22:23], v[22:23], 1.0 op_sel_hi:[1,0]
	v_pk_mul_f32 v[20:21], v[24:25], v[20:21]
	s_nop 0
	s_nop 0
	v_rcp_f32_e32 v24, v23
	s_nop 0
	v_mul_f32_e32 v23, v27, v24
	s_nop 0
	s_nop 0
	s_nop 0
	v_rcp_f32_e32 v24, v22
	s_nop 0
	v_mul_f32_e32 v22, v26, v24
	s_nop 0
	v_pk_mul_f32 v[20:21], v[20:21], v[22:23]
	s_nop 0
	v_cvt_pk_bf16_f32 v19, v20, v21
	global_store_dwordx2 v[16:17], v[18:19], off offset:48
	s_waitcnt vmcnt(4)
	v_mov_b64_e32 v[22:23], v[162:163]
	v_mov_b64_e32 v[18:19], v[184:185]
	v_mov_b64_e32 v[20:21], v[186:187]
	v_lshlrev_b32_e32 v26, 16, v22
	v_and_b32_e32 v22, 0xffff0000, v22
	v_mul_f32_e32 v24, 0xbfb8aa3b, v26
	v_pk_mul_f32 v[0:1], v[0:1], v[18:19]
	v_mul_f32_e32 v18, 0xbfb8aa3b, v22
	v_exp_f32_e32 v24, v24
	v_exp_f32_e32 v25, v18
	v_pk_mul_f32 v[2:3], v[2:3], v[20:21]
	v_pk_add_f32 v[18:19], v[24:25], 1.0 op_sel_hi:[1,0]
	s_nop 0
	s_nop 0
	s_nop 0
	v_rcp_f32_e32 v24, v19
	s_nop 0
	v_mul_f32_e32 v19, v22, v24
	s_nop 0
	s_nop 0
	s_nop 0
	v_rcp_f32_e32 v22, v18
	s_nop 0
	v_mul_f32_e32 v18, v26, v22
	s_nop 0
	v_lshlrev_b32_e32 v22, 16, v23
	v_and_b32_e32 v23, 0xffff0000, v23
	v_pk_mul_f32 v[0:1], v[0:1], v[18:19]
	v_mul_f32_e32 v18, 0xbfb8aa3b, v22
	v_mul_f32_e32 v19, 0xbfb8aa3b, v23
	v_exp_f32_e32 v18, v18
	v_exp_f32_e32 v19, v19
	v_cvt_pk_bf16_f32 v0, v0, v1
	v_pk_add_f32 v[18:19], v[18:19], 1.0 op_sel_hi:[1,0]
	s_nop 0
	s_nop 0
	s_nop 0
	v_rcp_f32_e32 v20, v19
	s_nop 0
	v_mul_f32_e32 v19, v23, v20
	s_nop 0
	s_nop 0
	s_nop 0
	v_rcp_f32_e32 v20, v18
	s_nop 0
	v_mul_f32_e32 v18, v22, v20
	s_nop 0
	v_pk_mul_f32 v[2:3], v[2:3], v[18:19]
	s_nop 0
	v_cvt_pk_bf16_f32 v1, v2, v3
	global_store_dwordx2 v[16:17], v[0:1], off offset:64
	s_waitcnt vmcnt(5)
	v_mov_b64_e32 v[18:19], v[164:165]
	v_mov_b64_e32 v[0:1], v[188:189]
	v_mov_b64_e32 v[2:3], v[190:191]
	v_lshlrev_b32_e32 v22, 16, v18
	v_and_b32_e32 v18, 0xffff0000, v18
	v_mul_f32_e32 v20, 0xbfb8aa3b, v22
	v_pk_mul_f32 v[0:1], v[4:5], v[0:1]
	v_mul_f32_e32 v4, 0xbfb8aa3b, v18
	v_exp_f32_e32 v20, v20
	v_exp_f32_e32 v21, v4
	s_nop 0
	v_pk_add_f32 v[4:5], v[20:21], 1.0 op_sel_hi:[1,0]
	s_nop 0
	s_nop 0
	s_nop 0
	v_rcp_f32_e32 v20, v5
	s_nop 0
	v_mul_f32_e32 v5, v18, v20
	s_nop 0
	s_nop 0
	s_nop 0
	v_rcp_f32_e32 v18, v4
	s_nop 0
	v_mul_f32_e32 v4, v22, v18
	s_nop 0
	v_pk_mul_f32 v[0:1], v[0:1], v[4:5]
	v_pk_add_f32 v[4:5], v[6:7], v[36:37] op_sel_hi:[1,0] neg_lo:[0,1] neg_hi:[0,1]
	v_lshlrev_b32_e32 v18, 16, v19
	v_and_b32_e32 v19, 0xffff0000, v19
	v_pk_mul_f32 v[4:5], v[4:5], v[38:39] op_sel_hi:[1,0]
	v_mul_f32_e32 v6, 0xbfb8aa3b, v18
	v_pk_mul_f32 v[2:3], v[4:5], v[2:3]
	v_mul_f32_e32 v4, 0xbfb8aa3b, v19
	v_exp_f32_e32 v6, v6
	v_exp_f32_e32 v7, v4
	v_cvt_pk_bf16_f32 v0, v0, v1
	v_pk_add_f32 v[4:5], v[6:7], 1.0 op_sel_hi:[1,0]
	s_nop 0
	s_nop 0
	s_nop 0
	v_rcp_f32_e32 v6, v5
	s_nop 0
	v_mul_f32_e32 v5, v19, v6
	s_nop 0
	s_nop 0
	s_nop 0
	v_rcp_f32_e32 v6, v4
	s_nop 0
	v_mul_f32_e32 v4, v18, v6
	s_nop 0
	v_pk_mul_f32 v[2:3], v[2:3], v[4:5]
	v_pk_add_f32 v[6:7], v[8:9], v[36:37] op_sel_hi:[1,0] neg_lo:[0,1] neg_hi:[0,1]
	v_cvt_pk_bf16_f32 v1, v2, v3
	global_store_dwordx2 v[16:17], v[0:1], off offset:80
	s_waitcnt vmcnt(6)
	v_mov_b64_e32 v[4:5], v[166:167]
	v_mov_b64_e32 v[0:1], v[206:207]
	v_mov_b64_e32 v[2:3], v[208:209]
	v_pk_mul_f32 v[6:7], v[6:7], v[38:39] op_sel_hi:[1,0]
	v_lshlrev_b32_e32 v18, 16, v4
	v_and_b32_e32 v4, 0xffff0000, v4
	v_mul_f32_e32 v8, 0xbfb8aa3b, v18
	v_pk_mul_f32 v[0:1], v[6:7], v[0:1]
	v_mul_f32_e32 v6, 0xbfb8aa3b, v4
	v_exp_f32_e32 v8, v8
	v_exp_f32_e32 v9, v6
	s_nop 0
	v_pk_add_f32 v[6:7], v[8:9], 1.0 op_sel_hi:[1,0]
	s_nop 0
	s_nop 0
	s_nop 0
	v_rcp_f32_e32 v8, v7
	s_nop 0
	v_mul_f32_e32 v7, v4, v8
	s_nop 0
	s_nop 0
	v_lshlrev_b32_e32 v8, 16, v5
	v_and_b32_e32 v9, 0xffff0000, v5
	s_nop 0
	v_rcp_f32_e32 v4, v6
	s_nop 0
	v_mul_f32_e32 v6, v18, v4
	s_nop 0
	v_mul_f32_e32 v4, 0xbfb8aa3b, v8
	v_mul_f32_e32 v5, 0xbfb8aa3b, v9
	v_exp_f32_e32 v4, v4
	v_exp_f32_e32 v5, v5
	v_pk_mul_f32 v[0:1], v[0:1], v[6:7]
	v_pk_add_f32 v[6:7], v[10:11], v[36:37] op_sel_hi:[1,0] neg_lo:[0,1] neg_hi:[0,1]
	v_cvt_pk_bf16_f32 v0, v0, v1
	v_pk_mul_f32 v[6:7], v[6:7], v[38:39] op_sel_hi:[1,0]
	v_pk_add_f32 v[4:5], v[4:5], 1.0 op_sel_hi:[1,0]
	v_pk_mul_f32 v[2:3], v[6:7], v[2:3]
	s_nop 0
	s_nop 0
	v_rcp_f32_e32 v6, v5
	s_nop 0
	v_mul_f32_e32 v5, v9, v6
	s_nop 0
	s_nop 0
	s_nop 0
	v_rcp_f32_e32 v6, v4
	s_nop 0
	v_mul_f32_e32 v4, v8, v6
	s_nop 0
	v_pk_mul_f32 v[2:3], v[2:3], v[4:5]
	v_pk_add_f32 v[6:7], v[12:13], v[36:37] op_sel_hi:[1,0] neg_lo:[0,1] neg_hi:[0,1]
	v_cvt_pk_bf16_f32 v1, v2, v3
	global_store_dwordx2 v[16:17], v[0:1], off offset:96
	s_waitcnt vmcnt(7)
	v_mov_b64_e32 v[4:5], v[168:169]
	v_mov_b64_e32 v[0:1], v[210:211]
	v_mov_b64_e32 v[2:3], v[212:213]
	v_pk_mul_f32 v[6:7], v[6:7], v[38:39] op_sel_hi:[1,0]
	v_lshlrev_b32_e32 v10, 16, v4
	v_and_b32_e32 v4, 0xffff0000, v4
	v_mul_f32_e32 v8, 0xbfb8aa3b, v10
	v_pk_mul_f32 v[0:1], v[6:7], v[0:1]
	v_mul_f32_e32 v6, 0xbfb8aa3b, v4
	v_exp_f32_e32 v8, v8
	v_exp_f32_e32 v9, v6
	s_nop 0
	v_pk_add_f32 v[6:7], v[8:9], 1.0 op_sel_hi:[1,0]
	s_nop 0
	s_nop 0
	s_nop 0
	v_rcp_f32_e32 v8, v7
	s_nop 0
	v_mul_f32_e32 v7, v4, v8
	s_nop 0
	s_nop 0
	v_lshlrev_b32_e32 v8, 16, v5
	v_and_b32_e32 v9, 0xffff0000, v5
	s_nop 0
	v_rcp_f32_e32 v4, v6
	s_nop 0
	v_mul_f32_e32 v6, v10, v4
	s_nop 0
	v_mul_f32_e32 v4, 0xbfb8aa3b, v8
	v_mul_f32_e32 v5, 0xbfb8aa3b, v9
	v_exp_f32_e32 v4, v4
	v_exp_f32_e32 v5, v5
	v_pk_mul_f32 v[0:1], v[0:1], v[6:7]
	v_pk_add_f32 v[6:7], v[14:15], v[36:37] op_sel_hi:[1,0] neg_lo:[0,1] neg_hi:[0,1]
	v_cvt_pk_bf16_f32 v0, v0, v1
	v_pk_mul_f32 v[6:7], v[6:7], v[38:39] op_sel_hi:[1,0]
	v_pk_add_f32 v[4:5], v[4:5], 1.0 op_sel_hi:[1,0]
	v_pk_mul_f32 v[2:3], v[6:7], v[2:3]
	s_nop 0
	s_nop 0
	v_rcp_f32_e32 v6, v5
	s_nop 0
	v_mul_f32_e32 v5, v9, v6
	s_nop 0
	s_nop 0
	s_nop 0
	v_rcp_f32_e32 v6, v4
	s_nop 0
	v_mul_f32_e32 v4, v8, v6
	s_nop 0
	v_pk_mul_f32 v[2:3], v[2:3], v[4:5]
	s_nop 0
	v_cvt_pk_bf16_f32 v1, v2, v3
	global_store_dwordx2 v[16:17], v[0:1], off offset:112
	s_cbranch_scc1 .LBB0_872

.LBB0_966:
	v_add_f32_e32 v64, 0x358637bd, v65
	v_cmp_gt_f32_e32 vcc, s73, v64
	v_mul_f32_e32 v65, 0x4f800000, v64
	s_lshl_b64 s[6:7], s[36:37], 2
	v_cndmask_b32_e32 v64, v64, v65, vcc
	v_sqrt_f32_e32 v65, v64
	s_add_u32 s8, s30, s6
	s_addc_u32 s9, s31, s7
	s_lshl_b64 s[6:7], s[26:27], 2
	v_add_u32_e32 v66, -1, v65
	s_waitcnt lgkmcnt(0)
	v_fma_f32 v67, -v66, v65, v64
	v_cmp_ge_f32_e64 s[40:41], 0, v67
	v_add_u32_e32 v67, 1, v65
	s_add_u32 s22, s8, s6
	v_cndmask_b32_e64 v66, v65, v66, s[40:41]
	v_fma_f32 v65, -v67, v65, v64
	v_cmp_lt_f32_e64 s[40:41], 0, v65
	s_addc_u32 s23, s9, s7
	v_or_b32_e32 v192, s5, v138
	v_cndmask_b32_e64 v65, v66, v67, s[40:41]
	v_mul_f32_e32 v66, 0x37800000, v65
	v_cndmask_b32_e32 v65, v65, v66, vcc
	v_cmp_class_f32_e32 vcc, v64, v236
	s_lshl_b32 s42, s4, 8
	v_ashrrev_i32_e32 v125, 31, v124
	v_cndmask_b32_e32 v64, v65, v64, vcc
	v_ashrrev_i32_e32 v129, 31, v128
	v_lshlrev_b64 v[70:71], 1, v[124:125]
	s_ashr_i32 s43, s42, 31
	s_nop 0
	v_rcp_f32_e32 v74, v64
	s_nop 0
	v_mov_b64_e32 v[64:65], s[34:35]
	v_mad_i64_i32 v[64:65], s[4:5], v128, s84, v[64:65]
	v_lshl_add_u64 v[64:65], v[192:193], 1, v[64:65]
	v_lshlrev_b64 v[66:67], 11, v[128:129]
	v_lshl_add_u64 v[76:77], v[64:65], 0, v[70:71]
	v_lshl_add_u64 v[66:67], s[20:21], 0, v[66:67]
	global_load_dwordx2 v[80:81], v[76:77], off
	v_lshl_add_u64 v[66:67], s[42:43], 1, v[66:67]
	v_lshl_add_u64 v[68:69], v[124:125], 2, s[22:23]
	v_lshl_add_u64 v[78:79], s[26:27], 1, v[66:67]
	global_load_dwordx4 v[64:67], v[68:69], off
	global_load_dwordx2 v[156:157], v[76:77], off offset:16
	global_load_dwordx2 v[158:159], v[76:77], off offset:32
	global_load_dwordx2 v[160:161], v[76:77], off offset:48
	global_load_dwordx2 v[162:163], v[76:77], off offset:64
	global_load_dwordx2 v[164:165], v[76:77], off offset:80
	global_load_dwordx2 v[166:167], v[76:77], off offset:96
	global_load_dwordx2 v[168:169], v[76:77], off offset:112
	global_load_dwordx4 v[172:175], v[68:69], off offset:32
	global_load_dwordx4 v[176:179], v[68:69], off offset:64
	global_load_dwordx4 v[180:183], v[68:69], off offset:96
	global_load_dwordx4 v[184:187], v[68:69], off offset:128
	global_load_dwordx4 v[188:191], v[68:69], off offset:160
	global_load_dwordx4 v[206:209], v[68:69], off offset:192
	global_load_dwordx4 v[210:213], v[68:69], off offset:224
	v_pk_add_f32 v[48:49], v[48:49], v[72:73] op_sel_hi:[1,0] neg_lo:[0,1] neg_hi:[0,1]
	v_pk_add_f32 v[50:51], v[50:51], v[72:73] op_sel_hi:[1,0] neg_lo:[0,1] neg_hi:[0,1]
	v_pk_add_f32 v[56:57], v[56:57], v[72:73] op_sel_hi:[1,0] neg_lo:[0,1] neg_hi:[0,1]
	v_pk_add_f32 v[32:33], v[32:33], v[72:73] op_sel_hi:[1,0] neg_lo:[0,1] neg_hi:[0,1]
	v_pk_add_f32 v[34:35], v[34:35], v[72:73] op_sel_hi:[1,0] neg_lo:[0,1] neg_hi:[0,1]
	v_pk_add_f32 v[36:37], v[36:37], v[72:73] op_sel_hi:[1,0] neg_lo:[0,1] neg_hi:[0,1]
	s_mov_b64 s[22:23], -1
	s_waitcnt vmcnt(15)
	v_lshlrev_b32_e32 v75, 16, v80
	v_and_b32_e32 v80, 0xffff0000, v80
	v_pk_mul_f32 v[48:49], v[48:49], v[74:75] op_sel_hi:[1,0]
	v_mul_f32_e32 v82, 0xbfb8aa3b, v75
	s_waitcnt vmcnt(14)
	v_pk_mul_f32 v[48:49], v[64:65], v[48:49]
	v_mul_f32_e32 v64, 0xbfb8aa3b, v80
	v_exp_f32_e32 v82, v82
	v_exp_f32_e32 v83, v64
	s_nop 0
	v_pk_add_f32 v[64:65], v[82:83], 1.0 op_sel_hi:[1,0]
	s_nop 0
	s_nop 0
	s_nop 0
	v_rcp_f32_e32 v82, v65
	s_nop 0
	v_mul_f32_e32 v65, v80, v82
	s_nop 0
	s_nop 0
	s_nop 0
	v_rcp_f32_e32 v80, v64
	s_nop 0
	v_mul_f32_e32 v64, v75, v80
	s_nop 0
	v_lshlrev_b32_e32 v75, 16, v81
	v_and_b32_e32 v80, 0xffff0000, v81
	v_pk_mul_f32 v[48:49], v[48:49], v[64:65]
	v_mul_f32_e32 v64, 0xbfb8aa3b, v75
	v_mul_f32_e32 v65, 0xbfb8aa3b, v80
	v_exp_f32_e32 v64, v64
	v_exp_f32_e32 v65, v65
	v_pk_mul_f32 v[50:51], v[50:51], v[74:75] op_sel_hi:[1,0]
	v_pk_add_f32 v[64:65], v[64:65], 1.0 op_sel_hi:[1,0]
	v_pk_mul_f32 v[50:51], v[66:67], v[50:51]
	s_nop 0
	s_nop 0
	v_rcp_f32_e32 v66, v65
	s_nop 0
	v_mul_f32_e32 v65, v80, v66
	s_nop 0
	s_nop 0
	s_nop 0
	v_rcp_f32_e32 v66, v64
	s_nop 0
	v_mul_f32_e32 v64, v75, v66
	s_nop 0
	v_pk_mul_f32 v[50:51], v[50:51], v[64:65]
	v_cvt_pk_bf16_f32 v64, v48, v49
	v_cvt_pk_bf16_f32 v65, v50, v51
	v_lshl_add_u64 v[48:49], v[78:79], 0, v[70:71]
	global_store_dwordx2 v[48:49], v[64:65], off
	s_waitcnt vmcnt(1)
	v_mov_b64_e32 v[78:79], v[156:157]
	v_mov_b64_e32 v[64:65], v[172:173]
	v_mov_b64_e32 v[66:67], v[174:175]
	v_pk_add_f32 v[50:51], v[52:53], v[72:73] op_sel_hi:[1,0] neg_lo:[0,1] neg_hi:[0,1]
	v_lshlrev_b32_e32 v75, 16, v78
	v_and_b32_e32 v78, 0xffff0000, v78
	v_mul_f32_e32 v52, 0xbfb8aa3b, v75
	v_mul_f32_e32 v53, 0xbfb8aa3b, v78
	v_exp_f32_e32 v52, v52
	v_exp_f32_e32 v53, v53
	v_pk_mul_f32 v[50:51], v[50:51], v[74:75] op_sel_hi:[1,0]
	v_pk_add_f32 v[52:53], v[52:53], 1.0 op_sel_hi:[1,0]
	v_pk_mul_f32 v[50:51], v[50:51], v[64:65]
	s_nop 0
	s_nop 0
	v_rcp_f32_e32 v64, v53
	s_nop 0
	v_mul_f32_e32 v53, v78, v64
	s_nop 0
	s_nop 0
	s_nop 0
	v_rcp_f32_e32 v64, v52
	s_nop 0
	v_mul_f32_e32 v52, v75, v64
	s_nop 0
	v_lshlrev_b32_e32 v64, 16, v79
	v_and_b32_e32 v65, 0xffff0000, v79
	v_pk_mul_f32 v[50:51], v[50:51], v[52:53]
	v_pk_add_f32 v[52:53], v[54:55], v[72:73] op_sel_hi:[1,0] neg_lo:[0,1] neg_hi:[0,1]
	v_mul_f32_e32 v54, 0xbfb8aa3b, v64
	v_mul_f32_e32 v55, 0xbfb8aa3b, v65
	v_exp_f32_e32 v54, v54
	v_exp_f32_e32 v55, v55
	v_pk_mul_f32 v[52:53], v[52:53], v[74:75] op_sel_hi:[1,0]
	v_cvt_pk_bf16_f32 v50, v50, v51
	v_pk_mul_f32 v[52:53], v[52:53], v[66:67]
	v_pk_add_f32 v[54:55], v[54:55], 1.0 op_sel_hi:[1,0]
	s_nop 0
	s_nop 0
	s_nop 0
	v_rcp_f32_e32 v66, v55
	s_nop 0
	v_mul_f32_e32 v55, v65, v66
	s_nop 0
	s_nop 0
	s_nop 0
	v_rcp_f32_e32 v65, v54
	s_nop 0
	v_mul_f32_e32 v54, v64, v65
	s_nop 0
	v_pk_mul_f32 v[52:53], v[52:53], v[54:55]
	v_pk_mul_f32 v[56:57], v[56:57], v[74:75] op_sel_hi:[1,0]
	v_cvt_pk_bf16_f32 v51, v52, v53
	global_store_dwordx2 v[48:49], v[50:51], off offset:16
	s_waitcnt vmcnt(2)
	v_mov_b64_e32 v[54:55], v[158:159]
	v_mov_b64_e32 v[50:51], v[176:177]
	v_mov_b64_e32 v[52:53], v[178:179]
	v_lshlrev_b32_e32 v66, 16, v54
	v_and_b32_e32 v54, 0xffff0000, v54
	v_mul_f32_e32 v64, 0xbfb8aa3b, v66
	v_pk_mul_f32 v[50:51], v[56:57], v[50:51]
	v_mul_f32_e32 v56, 0xbfb8aa3b, v54
	v_exp_f32_e32 v64, v64
	v_exp_f32_e32 v65, v56
	s_nop 0
	v_pk_add_f32 v[56:57], v[64:65], 1.0 op_sel_hi:[1,0]
	s_nop 0
	s_nop 0
	s_nop 0
	v_rcp_f32_e32 v64, v57
	s_nop 0
	v_mul_f32_e32 v57, v54, v64
	s_nop 0
	s_nop 0
	s_nop 0
	v_rcp_f32_e32 v54, v56
	s_nop 0
	v_mul_f32_e32 v56, v66, v54
	s_nop 0
	v_pk_mul_f32 v[50:51], v[50:51], v[56:57]
	v_pk_add_f32 v[56:57], v[58:59], v[72:73] op_sel_hi:[1,0] neg_lo:[0,1] neg_hi:[0,1]
	v_lshlrev_b32_e32 v58, 16, v55
	v_and_b32_e32 v59, 0xffff0000, v55
	v_mul_f32_e32 v54, 0xbfb8aa3b, v58
	v_mul_f32_e32 v55, 0xbfb8aa3b, v59
	v_exp_f32_e32 v54, v54
	v_exp_f32_e32 v55, v55
	v_pk_mul_f32 v[56:57], v[56:57], v[74:75] op_sel_hi:[1,0]
	v_cvt_pk_bf16_f32 v50, v50, v51
	v_pk_mul_f32 v[52:53], v[56:57], v[52:53]
	v_pk_add_f32 v[54:55], v[54:55], 1.0 op_sel_hi:[1,0]
	v_pk_mul_f32 v[32:33], v[32:33], v[74:75] op_sel_hi:[1,0]
	v_pk_mul_f32 v[34:35], v[34:35], v[74:75] op_sel_hi:[1,0]
	v_pk_mul_f32 v[36:37], v[36:37], v[74:75] op_sel_hi:[1,0]
	s_nop 0
	v_rcp_f32_e32 v56, v55
	s_nop 0
	v_mul_f32_e32 v55, v59, v56
	s_nop 0
	s_nop 0
	s_nop 0
	v_rcp_f32_e32 v56, v54
	s_nop 0
	v_mul_f32_e32 v54, v58, v56
	s_nop 0
	v_pk_mul_f32 v[52:53], v[52:53], v[54:55]
	v_pk_add_f32 v[56:57], v[60:61], v[72:73] op_sel_hi:[1,0] neg_lo:[0,1] neg_hi:[0,1]
	v_cvt_pk_bf16_f32 v51, v52, v53
	global_store_dwordx2 v[48:49], v[50:51], off offset:32
	s_waitcnt vmcnt(3)
	v_mov_b64_e32 v[54:55], v[160:161]
	v_mov_b64_e32 v[50:51], v[180:181]
	v_mov_b64_e32 v[52:53], v[182:183]
	v_pk_mul_f32 v[56:57], v[56:57], v[74:75] op_sel_hi:[1,0]
	v_lshlrev_b32_e32 v60, 16, v54
	v_and_b32_e32 v54, 0xffff0000, v54
	v_mul_f32_e32 v58, 0xbfb8aa3b, v60
	v_pk_mul_f32 v[50:51], v[56:57], v[50:51]
	v_mul_f32_e32 v56, 0xbfb8aa3b, v54
	v_exp_f32_e32 v58, v58
	v_exp_f32_e32 v59, v56
	s_nop 0
	v_pk_add_f32 v[56:57], v[58:59], 1.0 op_sel_hi:[1,0]
	s_nop 0
	s_nop 0
	s_nop 0
	v_rcp_f32_e32 v58, v57
	s_nop 0
	v_mul_f32_e32 v57, v54, v58
	s_nop 0
	s_nop 0
	v_lshlrev_b32_e32 v58, 16, v55
	v_and_b32_e32 v59, 0xffff0000, v55
	s_nop 0
	v_rcp_f32_e32 v54, v56
	s_nop 0
	v_mul_f32_e32 v56, v60, v54
	s_nop 0
	v_mul_f32_e32 v54, 0xbfb8aa3b, v58
	v_mul_f32_e32 v55, 0xbfb8aa3b, v59
	v_exp_f32_e32 v54, v54
	v_exp_f32_e32 v55, v55
	v_pk_mul_f32 v[50:51], v[50:51], v[56:57]
	v_pk_add_f32 v[56:57], v[62:63], v[72:73] op_sel_hi:[1,0] neg_lo:[0,1] neg_hi:[0,1]
	v_cvt_pk_bf16_f32 v50, v50, v51
	v_pk_mul_f32 v[56:57], v[56:57], v[74:75] op_sel_hi:[1,0]
	v_pk_add_f32 v[54:55], v[54:55], 1.0 op_sel_hi:[1,0]
	v_pk_mul_f32 v[52:53], v[56:57], v[52:53]
	s_nop 0
	s_nop 0
	v_rcp_f32_e32 v56, v55
	s_nop 0
	v_mul_f32_e32 v55, v59, v56
	s_nop 0
	s_nop 0
	s_nop 0
	v_rcp_f32_e32 v56, v54
	s_nop 0
	v_mul_f32_e32 v54, v58, v56
	s_nop 0
	v_pk_mul_f32 v[52:53], v[52:53], v[54:55]
	s_nop 0
	v_cvt_pk_bf16_f32 v51, v52, v53
	global_store_dwordx2 v[48:49], v[50:51], off offset:48
	s_waitcnt vmcnt(4)
	v_mov_b64_e32 v[54:55], v[162:163]
	v_mov_b64_e32 v[50:51], v[184:185]
	v_mov_b64_e32 v[52:53], v[186:187]
	v_lshlrev_b32_e32 v58, 16, v54
	v_and_b32_e32 v54, 0xffff0000, v54
	v_mul_f32_e32 v56, 0xbfb8aa3b, v58
	v_pk_mul_f32 v[32:33], v[32:33], v[50:51]
	v_mul_f32_e32 v50, 0xbfb8aa3b, v54
	v_exp_f32_e32 v56, v56
	v_exp_f32_e32 v57, v50
	v_pk_mul_f32 v[34:35], v[34:35], v[52:53]
	v_pk_add_f32 v[50:51], v[56:57], 1.0 op_sel_hi:[1,0]
	s_nop 0
	s_nop 0
	s_nop 0
	v_rcp_f32_e32 v56, v51
	s_nop 0
	v_mul_f32_e32 v51, v54, v56
	s_nop 0
	s_nop 0
	s_nop 0
	v_rcp_f32_e32 v54, v50
	s_nop 0
	v_mul_f32_e32 v50, v58, v54
	s_nop 0
	v_lshlrev_b32_e32 v54, 16, v55
	v_and_b32_e32 v55, 0xffff0000, v55
	v_pk_mul_f32 v[32:33], v[32:33], v[50:51]
	v_mul_f32_e32 v50, 0xbfb8aa3b, v54
	v_mul_f32_e32 v51, 0xbfb8aa3b, v55
	v_exp_f32_e32 v50, v50
	v_exp_f32_e32 v51, v51
	v_cvt_pk_bf16_f32 v32, v32, v33
	v_pk_add_f32 v[50:51], v[50:51], 1.0 op_sel_hi:[1,0]
	s_nop 0
	s_nop 0
	s_nop 0
	v_rcp_f32_e32 v52, v51
	s_nop 0
	v_mul_f32_e32 v51, v55, v52
	s_nop 0
	s_nop 0
	s_nop 0
	v_rcp_f32_e32 v52, v50
	s_nop 0
	v_mul_f32_e32 v50, v54, v52
	s_nop 0
	v_pk_mul_f32 v[34:35], v[34:35], v[50:51]
	s_nop 0
	v_cvt_pk_bf16_f32 v33, v34, v35
	global_store_dwordx2 v[48:49], v[32:33], off offset:64
	s_waitcnt vmcnt(5)
	v_mov_b64_e32 v[50:51], v[164:165]
	v_mov_b64_e32 v[32:33], v[188:189]
	v_mov_b64_e32 v[34:35], v[190:191]
	v_lshlrev_b32_e32 v54, 16, v50
	v_and_b32_e32 v50, 0xffff0000, v50
	v_mul_f32_e32 v52, 0xbfb8aa3b, v54
	v_pk_mul_f32 v[32:33], v[36:37], v[32:33]
	v_mul_f32_e32 v36, 0xbfb8aa3b, v50
	v_exp_f32_e32 v52, v52
	v_exp_f32_e32 v53, v36
	s_nop 0
	v_pk_add_f32 v[36:37], v[52:53], 1.0 op_sel_hi:[1,0]
	s_nop 0
	s_nop 0
	s_nop 0
	v_rcp_f32_e32 v52, v37
	s_nop 0
	v_mul_f32_e32 v37, v50, v52
	s_nop 0
	s_nop 0
	s_nop 0
	v_rcp_f32_e32 v50, v36
	s_nop 0
	v_mul_f32_e32 v36, v54, v50
	s_nop 0
	v_pk_mul_f32 v[32:33], v[32:33], v[36:37]
	v_pk_add_f32 v[36:37], v[38:39], v[72:73] op_sel_hi:[1,0] neg_lo:[0,1] neg_hi:[0,1]
	v_lshlrev_b32_e32 v50, 16, v51
	v_and_b32_e32 v51, 0xffff0000, v51
	v_pk_mul_f32 v[36:37], v[36:37], v[74:75] op_sel_hi:[1,0]
	v_mul_f32_e32 v38, 0xbfb8aa3b, v50
	v_pk_mul_f32 v[34:35], v[36:37], v[34:35]
	v_mul_f32_e32 v36, 0xbfb8aa3b, v51
	v_exp_f32_e32 v38, v38
	v_exp_f32_e32 v39, v36
	v_cvt_pk_bf16_f32 v32, v32, v33
	v_pk_add_f32 v[36:37], v[38:39], 1.0 op_sel_hi:[1,0]
	s_nop 0
	s_nop 0
	s_nop 0
	v_rcp_f32_e32 v38, v37
	s_nop 0
	v_mul_f32_e32 v37, v51, v38
	s_nop 0
	s_nop 0
	s_nop 0
	v_rcp_f32_e32 v38, v36
	s_nop 0
	v_mul_f32_e32 v36, v50, v38
	s_nop 0
	v_pk_mul_f32 v[34:35], v[34:35], v[36:37]
	v_pk_add_f32 v[38:39], v[40:41], v[72:73] op_sel_hi:[1,0] neg_lo:[0,1] neg_hi:[0,1]
	v_cvt_pk_bf16_f32 v33, v34, v35
	global_store_dwordx2 v[48:49], v[32:33], off offset:80
	s_waitcnt vmcnt(6)
	v_mov_b64_e32 v[36:37], v[166:167]
	v_mov_b64_e32 v[32:33], v[206:207]
	v_mov_b64_e32 v[34:35], v[208:209]
	v_pk_mul_f32 v[38:39], v[38:39], v[74:75] op_sel_hi:[1,0]
	v_lshlrev_b32_e32 v50, 16, v36
	v_and_b32_e32 v36, 0xffff0000, v36
	v_mul_f32_e32 v40, 0xbfb8aa3b, v50
	v_pk_mul_f32 v[32:33], v[38:39], v[32:33]
	v_mul_f32_e32 v38, 0xbfb8aa3b, v36
	v_exp_f32_e32 v40, v40
	v_exp_f32_e32 v41, v38
	s_nop 0
	v_pk_add_f32 v[38:39], v[40:41], 1.0 op_sel_hi:[1,0]
	s_nop 0
	s_nop 0
	s_nop 0
	v_rcp_f32_e32 v40, v39
	s_nop 0
	v_mul_f32_e32 v39, v36, v40
	s_nop 0
	s_nop 0
	v_lshlrev_b32_e32 v40, 16, v37
	v_and_b32_e32 v41, 0xffff0000, v37
	s_nop 0
	v_rcp_f32_e32 v36, v38
	s_nop 0
	v_mul_f32_e32 v38, v50, v36
	s_nop 0
	v_mul_f32_e32 v36, 0xbfb8aa3b, v40
	v_mul_f32_e32 v37, 0xbfb8aa3b, v41
	v_exp_f32_e32 v36, v36
	v_exp_f32_e32 v37, v37
	v_pk_mul_f32 v[32:33], v[32:33], v[38:39]
	v_pk_add_f32 v[38:39], v[42:43], v[72:73] op_sel_hi:[1,0] neg_lo:[0,1] neg_hi:[0,1]
	v_cvt_pk_bf16_f32 v32, v32, v33
	v_pk_mul_f32 v[38:39], v[38:39], v[74:75] op_sel_hi:[1,0]
	v_pk_add_f32 v[36:37], v[36:37], 1.0 op_sel_hi:[1,0]
	v_pk_mul_f32 v[34:35], v[38:39], v[34:35]
	s_nop 0
	s_nop 0
	v_rcp_f32_e32 v38, v37
	s_nop 0
	v_mul_f32_e32 v37, v41, v38
	s_nop 0
	s_nop 0
	s_nop 0
	v_rcp_f32_e32 v38, v36
	s_nop 0
	v_mul_f32_e32 v36, v40, v38
	s_nop 0
	v_pk_mul_f32 v[34:35], v[34:35], v[36:37]
	v_pk_add_f32 v[38:39], v[44:45], v[72:73] op_sel_hi:[1,0] neg_lo:[0,1] neg_hi:[0,1]
	v_cvt_pk_bf16_f32 v33, v34, v35
	global_store_dwordx2 v[48:49], v[32:33], off offset:96
	s_waitcnt vmcnt(7)
	v_mov_b64_e32 v[36:37], v[168:169]
	v_mov_b64_e32 v[32:33], v[210:211]
	v_mov_b64_e32 v[34:35], v[212:213]
	v_pk_mul_f32 v[38:39], v[38:39], v[74:75] op_sel_hi:[1,0]
	v_lshlrev_b32_e32 v42, 16, v36
	v_and_b32_e32 v36, 0xffff0000, v36
	v_mul_f32_e32 v40, 0xbfb8aa3b, v42
	v_pk_mul_f32 v[32:33], v[38:39], v[32:33]
	v_mul_f32_e32 v38, 0xbfb8aa3b, v36
	v_exp_f32_e32 v40, v40
	v_exp_f32_e32 v41, v38
	s_nop 0
	v_pk_add_f32 v[38:39], v[40:41], 1.0 op_sel_hi:[1,0]
	s_nop 0
	s_nop 0
	s_nop 0
	v_rcp_f32_e32 v40, v39
	s_nop 0
	v_mul_f32_e32 v39, v36, v40
	s_nop 0
	s_nop 0
	v_lshlrev_b32_e32 v40, 16, v37
	v_and_b32_e32 v41, 0xffff0000, v37
	s_nop 0
	v_rcp_f32_e32 v36, v38
	s_nop 0
	v_mul_f32_e32 v38, v42, v36
	s_nop 0
	v_mul_f32_e32 v36, 0xbfb8aa3b, v40
	v_mul_f32_e32 v37, 0xbfb8aa3b, v41
	v_exp_f32_e32 v36, v36
	v_exp_f32_e32 v37, v37
	v_pk_mul_f32 v[32:33], v[32:33], v[38:39]
	v_pk_add_f32 v[38:39], v[46:47], v[72:73] op_sel_hi:[1,0] neg_lo:[0,1] neg_hi:[0,1]
	v_cvt_pk_bf16_f32 v32, v32, v33
	v_pk_mul_f32 v[38:39], v[38:39], v[74:75] op_sel_hi:[1,0]
	v_pk_add_f32 v[36:37], v[36:37], 1.0 op_sel_hi:[1,0]
	v_pk_mul_f32 v[34:35], v[38:39], v[34:35]
	s_nop 0
	s_nop 0
	v_rcp_f32_e32 v38, v37
	s_nop 0
	v_mul_f32_e32 v37, v41, v38
	s_nop 0
	s_nop 0
	s_nop 0
	v_rcp_f32_e32 v38, v36
	s_nop 0
	v_mul_f32_e32 v36, v40, v38
	s_nop 0
	v_pk_mul_f32 v[34:35], v[34:35], v[36:37]
	s_and_b64 vcc, exec, s[38:39]
	v_cvt_pk_bf16_f32 v33, v34, v35
	v_mul_f32_e32 v35, v17, v17
	global_store_dwordx2 v[48:49], v[32:33], off offset:112
	v_add_f32_e32 v32, 0, v16
	v_fmac_f32_e32 v35, v16, v16
	v_add_f32_e32 v32, v17, v32
	v_fmac_f32_e32 v35, v18, v18
	v_add_f32_e32 v32, v18, v32
	v_fmac_f32_e32 v35, v19, v19
	v_add_f32_e32 v32, v19, v32
	v_fmac_f32_e32 v35, v20, v20
	v_add_f32_e32 v32, v20, v32
	v_fmac_f32_e32 v35, v21, v21
	v_add_f32_e32 v32, v21, v32
	v_fmac_f32_e32 v35, v22, v22
	v_add_f32_e32 v32, v22, v32
	v_fmac_f32_e32 v35, v23, v23
	v_add_f32_e32 v32, v23, v32
	v_fmac_f32_e32 v35, v24, v24
	v_add_f32_e32 v32, v24, v32
	v_fmac_f32_e32 v35, v25, v25
	v_add_f32_e32 v32, v25, v32
	v_fmac_f32_e32 v35, v26, v26
	v_add_f32_e32 v32, v26, v32
	v_fmac_f32_e32 v35, v27, v27
	v_add_f32_e32 v32, v27, v32
	v_fmac_f32_e32 v35, v28, v28
	v_add_f32_e32 v32, v28, v32
	v_fmac_f32_e32 v35, v29, v29
	v_add_f32_e32 v32, v29, v32
	v_fmac_f32_e32 v35, v30, v30
	v_add_f32_e32 v32, v30, v32
	v_fmac_f32_e32 v35, v31, v31
	v_add_f32_e32 v32, v31, v32
	v_fmac_f32_e32 v35, v0, v0
	v_add_f32_e32 v32, v0, v32
	v_fmac_f32_e32 v35, v1, v1
	v_add_f32_e32 v32, v1, v32
	v_fmac_f32_e32 v35, v2, v2
	v_add_f32_e32 v32, v2, v32
	v_fmac_f32_e32 v35, v3, v3
	v_add_f32_e32 v32, v3, v32
	v_fmac_f32_e32 v35, v4, v4
	v_add_f32_e32 v32, v4, v32
	v_fmac_f32_e32 v35, v5, v5
	v_add_f32_e32 v32, v5, v32
	v_fmac_f32_e32 v35, v6, v6
	v_add_f32_e32 v32, v6, v32
	v_fmac_f32_e32 v35, v7, v7
	v_add_f32_e32 v32, v7, v32
	v_fmac_f32_e32 v35, v8, v8
	v_add_f32_e32 v32, v8, v32
	v_fmac_f32_e32 v35, v9, v9
	v_add_f32_e32 v32, v9, v32
	v_fmac_f32_e32 v35, v10, v10
	v_add_f32_e32 v32, v10, v32
	v_fmac_f32_e32 v35, v11, v11
	v_add_f32_e32 v32, v11, v32
	v_fmac_f32_e32 v35, v12, v12
	v_add_f32_e32 v32, v12, v32
	v_fmac_f32_e32 v35, v13, v13
	v_add_f32_e32 v32, v13, v32
	v_fmac_f32_e32 v35, v14, v14
	v_add_f32_e32 v32, v14, v32
	v_fmac_f32_e32 v35, v15, v15
	v_add_f32_e32 v33, v15, v32
	ds_bpermute_b32 v32, v73, v35
	ds_bpermute_b32 v34, v73, v33
	s_waitcnt lgkmcnt(1)
	v_add_f32_e32 v32, v35, v32
	s_cbranch_vccnz .LBB0_968
	v_mul_f32_e32 v35, 0x3c800000, v32
	s_mov_b64 s[22:23], 0
